# P4 EpiGate epilogues (both GEMMs): gate/partial loads run 4 row blocks ahead in a register ring with counted vmcnt instead of a load+wait per 16-byte store
# speedup vs baseline: 1.0111x; 1.0045x over previous
; __device__ __forceinline__ unsigned cvt_pk_bf16(float lo, float hi) { unsigned r; asm volatile("v_cvt_pk_bf16_f32 %0, %1, %2" : "=v"(r) : "v"(lo), "v"(hi)); return r; }
; __device__ __forceinline__ float bf_lo(unsigned w) { return __uint_as_float(w << 16); }
; __device__ __forceinline__ float bf_hi(unsigned w) { return __uint_as_float(w & 0xffff0000u); }
;     __device__ __forceinline__ void operator()(const f32x4 (&acc)[2][2][4][2], const Unit& u, int wr, int wc, int fr, int fq) const {
;     ...
;             for (int m = 0; m < 4; ++m) { const size_t ro = (size_t)(row0 + ai * HALF + m * 16) * 2048 + col0;
; #pragma unroll
;                 for (int bj = 0; bj < 2; ++bj) { const size_t off = ro + bj * HALF; const u32x4 g = *(const u32x4*)(G + off);
;                     f32x4 v0 = acc[ai][bj][m][0], v1 = acc[ai][bj][m][1];
;                     v0[0] *= bf_lo(g.x); v0[1] *= bf_hi(g.x); v0[2] *= bf_lo(g.y); v0[3] *= bf_hi(g.y); v1[0] *= bf_lo(g.z); v1[1] *= bf_hi(g.z); v1[2] *= bf_lo(g.w); v1[3] *= bf_hi(g.w);
;                     if (MODE == 1) { const u32x4 p = *(const u32x4*)(O + off);
;                         v0[0] += bf_lo(p.x); v0[1] += bf_hi(p.x); v0[2] += bf_lo(p.y); v0[3] += bf_hi(p.y); v1[0] += bf_lo(p.z); v1[1] += bf_hi(p.z); v1[2] += bf_lo(p.w); v1[3] += bf_hi(p.w); }
;                     u32x4 w; w.x = cvt_pk_bf16(v0[0], v0[1]); w.y = cvt_pk_bf16(v0[2], v0[3]); w.z = cvt_pk_bf16(v1[0], v1[1]); w.w = cvt_pk_bf16(v1[2], v1[3]);
;                     *(u32x4*)(O + off) = w; } }
.LBB0_635:
	s_andn2_b64 vcc, exec, s[0:1]
	s_mov_b64 s[0:1], -1
	v_lshlrev_b32_e32 v144, 12, v160
	v_lshl_add_u32 v144, v162, 1, v144
	s_lshl_b32 s72, s42, 20
	s_lshl_b32 s73, s65, 9
	s_add_u32 s72, s72, s73
	s_add_u32 s66, s12, s72
	s_addc_u32 s67, s13, 0
	s_add_u32 s68, s6, s72
	s_addc_u32 s69, s7, 0
	global_load_dwordx4 v[168:171], v144, s[66:67]
	global_load_dwordx4 v[172:175], v144, s[66:67] offset:256
	s_add_u32 s66, s66, 0x10000
	s_addc_u32 s67, s67, 0
	global_load_dwordx4 v[184:187], v144, s[66:67]
	global_load_dwordx4 v[188:191], v144, s[66:67] offset:256
	s_add_u32 s66, s66, 0x10000
	s_addc_u32 s67, s67, 0
	global_load_dwordx4 v[200:203], v144, s[66:67]
	global_load_dwordx4 v[204:207], v144, s[66:67] offset:256
	s_add_u32 s66, s66, 0x10000
	s_addc_u32 s67, s67, 0
	global_load_dwordx4 v[216:219], v144, s[66:67]
	global_load_dwordx4 v[220:223], v144, s[66:67] offset:256
	s_add_u32 s66, s66, 0x50000
	s_addc_u32 s67, s67, 0
	s_waitcnt vmcnt(6)
	v_lshlrev_b32_e32 v236, 16, v168
	v_and_b32_e32 v237, 0xffff0000, v168
	v_lshlrev_b32_e32 v238, 16, v169
	v_and_b32_e32 v239, 0xffff0000, v169
	v_lshlrev_b32_e32 v240, 16, v170
	v_and_b32_e32 v241, 0xffff0000, v170
	v_lshlrev_b32_e32 v242, 16, v171
	v_and_b32_e32 v243, 0xffff0000, v171
	v_mul_f32_e32 v124, v124, v236
	v_mul_f32_e32 v125, v125, v237
	v_mul_f32_e32 v126, v126, v238
	v_mul_f32_e32 v127, v127, v239
	v_mul_f32_e32 v120, v120, v240
	v_mul_f32_e32 v121, v121, v241
	v_mul_f32_e32 v122, v122, v242
	v_mul_f32_e32 v123, v123, v243
	v_cvt_pk_bf16_f32 v124, v124, v125
	v_cvt_pk_bf16_f32 v125, v126, v127
	v_cvt_pk_bf16_f32 v126, v120, v121
	v_cvt_pk_bf16_f32 v127, v122, v123
	global_store_dwordx4 v144, v[124:127], s[68:69]
	v_lshlrev_b32_e32 v236, 16, v172
	v_and_b32_e32 v237, 0xffff0000, v172
	v_lshlrev_b32_e32 v238, 16, v173
	v_and_b32_e32 v239, 0xffff0000, v173
	v_lshlrev_b32_e32 v240, 16, v174
	v_and_b32_e32 v241, 0xffff0000, v174
	v_lshlrev_b32_e32 v242, 16, v175
	v_and_b32_e32 v243, 0xffff0000, v175
	v_mul_f32_e32 v116, v116, v236
	v_mul_f32_e32 v117, v117, v237
	v_mul_f32_e32 v118, v118, v238
	v_mul_f32_e32 v119, v119, v239
	v_mul_f32_e32 v112, v112, v240
	v_mul_f32_e32 v113, v113, v241
	v_mul_f32_e32 v114, v114, v242
	v_mul_f32_e32 v115, v115, v243
	v_cvt_pk_bf16_f32 v116, v116, v117
	v_cvt_pk_bf16_f32 v117, v118, v119
	v_cvt_pk_bf16_f32 v118, v112, v113
	v_cvt_pk_bf16_f32 v119, v114, v115
	global_store_dwordx4 v144, v[116:119], s[68:69] offset:256
	s_add_u32 s68, s68, 0x10000
	s_addc_u32 s69, s69, 0
	global_load_dwordx4 v[168:171], v144, s[66:67]
	global_load_dwordx4 v[172:175], v144, s[66:67] offset:256
	s_add_u32 s66, s66, 0x10000
	s_addc_u32 s67, s67, 0
	s_waitcnt vmcnt(8)
	v_lshlrev_b32_e32 v236, 16, v184
	v_and_b32_e32 v237, 0xffff0000, v184
	v_lshlrev_b32_e32 v238, 16, v185
	v_and_b32_e32 v239, 0xffff0000, v185
	v_lshlrev_b32_e32 v240, 16, v186
	v_and_b32_e32 v241, 0xffff0000, v186
	v_lshlrev_b32_e32 v242, 16, v187
	v_and_b32_e32 v243, 0xffff0000, v187
	v_mul_f32_e32 v108, v108, v236
	v_mul_f32_e32 v109, v109, v237
	v_mul_f32_e32 v110, v110, v238
	v_mul_f32_e32 v111, v111, v239
	v_mul_f32_e32 v104, v104, v240
	v_mul_f32_e32 v105, v105, v241
	v_mul_f32_e32 v106, v106, v242
	v_mul_f32_e32 v107, v107, v243
	v_cvt_pk_bf16_f32 v108, v108, v109
	v_cvt_pk_bf16_f32 v109, v110, v111
	v_cvt_pk_bf16_f32 v110, v104, v105
	v_cvt_pk_bf16_f32 v111, v106, v107
	global_store_dwordx4 v144, v[108:111], s[68:69]
	v_lshlrev_b32_e32 v236, 16, v188
	v_and_b32_e32 v237, 0xffff0000, v188
	v_lshlrev_b32_e32 v238, 16, v189
	v_and_b32_e32 v239, 0xffff0000, v189
	v_lshlrev_b32_e32 v240, 16, v190
	v_and_b32_e32 v241, 0xffff0000, v190
	v_lshlrev_b32_e32 v242, 16, v191
	v_and_b32_e32 v243, 0xffff0000, v191
	v_mul_f32_e32 v100, v100, v236
	v_mul_f32_e32 v101, v101, v237
	v_mul_f32_e32 v102, v102, v238
	v_mul_f32_e32 v103, v103, v239
	v_mul_f32_e32 v96, v96, v240
	v_mul_f32_e32 v97, v97, v241
	v_mul_f32_e32 v98, v98, v242
	v_mul_f32_e32 v99, v99, v243
	v_cvt_pk_bf16_f32 v100, v100, v101
	v_cvt_pk_bf16_f32 v101, v102, v103
	v_cvt_pk_bf16_f32 v102, v96, v97
	v_cvt_pk_bf16_f32 v103, v98, v99
	global_store_dwordx4 v144, v[100:103], s[68:69] offset:256
	s_add_u32 s68, s68, 0x10000
	s_addc_u32 s69, s69, 0
	global_load_dwordx4 v[184:187], v144, s[66:67]
	global_load_dwordx4 v[188:191], v144, s[66:67] offset:256
	s_add_u32 s66, s66, 0x10000
	s_addc_u32 s67, s67, 0
	s_waitcnt vmcnt(10)
	v_lshlrev_b32_e32 v236, 16, v200
	v_and_b32_e32 v237, 0xffff0000, v200
	v_lshlrev_b32_e32 v238, 16, v201
	v_and_b32_e32 v239, 0xffff0000, v201
	v_lshlrev_b32_e32 v240, 16, v202
	v_and_b32_e32 v241, 0xffff0000, v202
	v_lshlrev_b32_e32 v242, 16, v203
	v_and_b32_e32 v243, 0xffff0000, v203
	v_mul_f32_e32 v92, v92, v236
	v_mul_f32_e32 v93, v93, v237
	v_mul_f32_e32 v94, v94, v238
	v_mul_f32_e32 v95, v95, v239
	v_mul_f32_e32 v88, v88, v240
	v_mul_f32_e32 v89, v89, v241
	v_mul_f32_e32 v90, v90, v242
	v_mul_f32_e32 v91, v91, v243
	v_cvt_pk_bf16_f32 v92, v92, v93
	v_cvt_pk_bf16_f32 v93, v94, v95
	v_cvt_pk_bf16_f32 v94, v88, v89
	v_cvt_pk_bf16_f32 v95, v90, v91
	global_store_dwordx4 v144, v[92:95], s[68:69]
	v_lshlrev_b32_e32 v236, 16, v204
	v_and_b32_e32 v237, 0xffff0000, v204
	v_lshlrev_b32_e32 v238, 16, v205
	v_and_b32_e32 v239, 0xffff0000, v205
	v_lshlrev_b32_e32 v240, 16, v206
	v_and_b32_e32 v241, 0xffff0000, v206
	v_lshlrev_b32_e32 v242, 16, v207
	v_and_b32_e32 v243, 0xffff0000, v207
	v_mul_f32_e32 v84, v84, v236
	v_mul_f32_e32 v85, v85, v237
	v_mul_f32_e32 v86, v86, v238
	v_mul_f32_e32 v87, v87, v239
	v_mul_f32_e32 v80, v80, v240
	v_mul_f32_e32 v81, v81, v241
	v_mul_f32_e32 v82, v82, v242
	v_mul_f32_e32 v83, v83, v243
	v_cvt_pk_bf16_f32 v84, v84, v85
	v_cvt_pk_bf16_f32 v85, v86, v87
	v_cvt_pk_bf16_f32 v86, v80, v81
	v_cvt_pk_bf16_f32 v87, v82, v83
	global_store_dwordx4 v144, v[84:87], s[68:69] offset:256
	s_add_u32 s68, s68, 0x10000
	s_addc_u32 s69, s69, 0
	global_load_dwordx4 v[200:203], v144, s[66:67]
	global_load_dwordx4 v[204:207], v144, s[66:67] offset:256
	s_add_u32 s66, s66, 0x10000
	s_addc_u32 s67, s67, 0
	s_waitcnt vmcnt(12)
; __device__ __forceinline__ unsigned cvt_pk_bf16(float lo, float hi) { unsigned r; asm volatile("v_cvt_pk_bf16_f32 %0, %1, %2" : "=v"(r) : "v"(lo), "v"(hi)); return r; }
; __device__ __forceinline__ float bf_lo(unsigned w) { return __uint_as_float(w << 16); }
; __device__ __forceinline__ float bf_hi(unsigned w) { return __uint_as_float(w & 0xffff0000u); }
;     __device__ __forceinline__ void operator()(const f32x4 (&acc)[2][2][4][2], const Unit& u, int wr, int wc, int fr, int fq) const {
;     ...
;             for (int m = 0; m < 4; ++m) { const size_t ro = (size_t)(row0 + ai * HALF + m * 16) * 2048 + col0;
; #pragma unroll
;                 for (int bj = 0; bj < 2; ++bj) { const size_t off = ro + bj * HALF; const u32x4 g = *(const u32x4*)(G + off);
;                     f32x4 v0 = acc[ai][bj][m][0], v1 = acc[ai][bj][m][1];
;                     v0[0] *= bf_lo(g.x); v0[1] *= bf_hi(g.x); v0[2] *= bf_lo(g.y); v0[3] *= bf_hi(g.y); v1[0] *= bf_lo(g.z); v1[1] *= bf_hi(g.z); v1[2] *= bf_lo(g.w); v1[3] *= bf_hi(g.w);
;                     if (MODE == 1) { const u32x4 p = *(const u32x4*)(O + off);
;                         v0[0] += bf_lo(p.x); v0[1] += bf_hi(p.x); v0[2] += bf_lo(p.y); v0[3] += bf_hi(p.y); v1[0] += bf_lo(p.z); v1[1] += bf_hi(p.z); v1[2] += bf_lo(p.w); v1[3] += bf_hi(p.w); }
;                     u32x4 w; w.x = cvt_pk_bf16(v0[0], v0[1]); w.y = cvt_pk_bf16(v0[2], v0[3]); w.z = cvt_pk_bf16(v1[0], v1[1]); w.w = cvt_pk_bf16(v1[2], v1[3]);
;                     *(u32x4*)(O + off) = w; } }
	v_lshlrev_b32_e32 v236, 16, v216
	v_and_b32_e32 v237, 0xffff0000, v216
	v_lshlrev_b32_e32 v238, 16, v217
	v_and_b32_e32 v239, 0xffff0000, v217
	v_lshlrev_b32_e32 v240, 16, v218
	v_and_b32_e32 v241, 0xffff0000, v218
	v_lshlrev_b32_e32 v242, 16, v219
	v_and_b32_e32 v243, 0xffff0000, v219
	v_mul_f32_e32 v76, v76, v236
	v_mul_f32_e32 v77, v77, v237
	v_mul_f32_e32 v78, v78, v238
	v_mul_f32_e32 v79, v79, v239
	v_mul_f32_e32 v72, v72, v240
	v_mul_f32_e32 v73, v73, v241
	v_mul_f32_e32 v74, v74, v242
	v_mul_f32_e32 v75, v75, v243
	v_cvt_pk_bf16_f32 v76, v76, v77
	v_cvt_pk_bf16_f32 v77, v78, v79
	v_cvt_pk_bf16_f32 v78, v72, v73
	v_cvt_pk_bf16_f32 v79, v74, v75
	global_store_dwordx4 v144, v[76:79], s[68:69]
	v_lshlrev_b32_e32 v236, 16, v220
	v_and_b32_e32 v237, 0xffff0000, v220
	v_lshlrev_b32_e32 v238, 16, v221
	v_and_b32_e32 v239, 0xffff0000, v221
	v_lshlrev_b32_e32 v240, 16, v222
	v_and_b32_e32 v241, 0xffff0000, v222
	v_lshlrev_b32_e32 v242, 16, v223
	v_and_b32_e32 v243, 0xffff0000, v223
	v_mul_f32_e32 v68, v68, v236
	v_mul_f32_e32 v69, v69, v237
	v_mul_f32_e32 v70, v70, v238
	v_mul_f32_e32 v71, v71, v239
	v_mul_f32_e32 v64, v64, v240
	v_mul_f32_e32 v65, v65, v241
	v_mul_f32_e32 v66, v66, v242
	v_mul_f32_e32 v67, v67, v243
	v_cvt_pk_bf16_f32 v68, v68, v69
	v_cvt_pk_bf16_f32 v69, v70, v71
	v_cvt_pk_bf16_f32 v70, v64, v65
	v_cvt_pk_bf16_f32 v71, v66, v67
	global_store_dwordx4 v144, v[68:71], s[68:69] offset:256
	s_add_u32 s68, s68, 0x50000
	s_addc_u32 s69, s69, 0
	global_load_dwordx4 v[216:219], v144, s[66:67]
	global_load_dwordx4 v[220:223], v144, s[66:67] offset:256
	s_waitcnt vmcnt(12)
	v_lshlrev_b32_e32 v236, 16, v168
	v_and_b32_e32 v237, 0xffff0000, v168
	v_lshlrev_b32_e32 v238, 16, v169
	v_and_b32_e32 v239, 0xffff0000, v169
	v_lshlrev_b32_e32 v240, 16, v170
	v_and_b32_e32 v241, 0xffff0000, v170
	v_lshlrev_b32_e32 v242, 16, v171
	v_and_b32_e32 v243, 0xffff0000, v171
	v_mul_f32_e32 v60, v60, v236
	v_mul_f32_e32 v61, v61, v237
	v_mul_f32_e32 v62, v62, v238
	v_mul_f32_e32 v63, v63, v239
	v_mul_f32_e32 v56, v56, v240
	v_mul_f32_e32 v57, v57, v241
	v_mul_f32_e32 v58, v58, v242
	v_mul_f32_e32 v59, v59, v243
	v_cvt_pk_bf16_f32 v60, v60, v61
	v_cvt_pk_bf16_f32 v61, v62, v63
	v_cvt_pk_bf16_f32 v62, v56, v57
	v_cvt_pk_bf16_f32 v63, v58, v59
	global_store_dwordx4 v144, v[60:63], s[68:69]
	v_lshlrev_b32_e32 v236, 16, v172
	v_and_b32_e32 v237, 0xffff0000, v172
	v_lshlrev_b32_e32 v238, 16, v173
	v_and_b32_e32 v239, 0xffff0000, v173
	v_lshlrev_b32_e32 v240, 16, v174
	v_and_b32_e32 v241, 0xffff0000, v174
	v_lshlrev_b32_e32 v242, 16, v175
	v_and_b32_e32 v243, 0xffff0000, v175
	v_mul_f32_e32 v52, v52, v236
	v_mul_f32_e32 v53, v53, v237
	v_mul_f32_e32 v54, v54, v238
	v_mul_f32_e32 v55, v55, v239
	v_mul_f32_e32 v48, v48, v240
	v_mul_f32_e32 v49, v49, v241
	v_mul_f32_e32 v50, v50, v242
	v_mul_f32_e32 v51, v51, v243
	v_cvt_pk_bf16_f32 v52, v52, v53
	v_cvt_pk_bf16_f32 v53, v54, v55
	v_cvt_pk_bf16_f32 v54, v48, v49
	v_cvt_pk_bf16_f32 v55, v50, v51
	global_store_dwordx4 v144, v[52:55], s[68:69] offset:256
	s_add_u32 s68, s68, 0x10000
	s_addc_u32 s69, s69, 0
	s_waitcnt vmcnt(10)
; __device__ __forceinline__ unsigned cvt_pk_bf16(float lo, float hi) { unsigned r; asm volatile("v_cvt_pk_bf16_f32 %0, %1, %2" : "=v"(r) : "v"(lo), "v"(hi)); return r; }
; __device__ __forceinline__ float bf_lo(unsigned w) { return __uint_as_float(w << 16); }
; __device__ __forceinline__ float bf_hi(unsigned w) { return __uint_as_float(w & 0xffff0000u); }
;     __device__ __forceinline__ void operator()(const f32x4 (&acc)[2][2][4][2], const Unit& u, int wr, int wc, int fr, int fq) const {
;     ...
;             for (int m = 0; m < 4; ++m) { const size_t ro = (size_t)(row0 + ai * HALF + m * 16) * 2048 + col0;
; #pragma unroll
;                 for (int bj = 0; bj < 2; ++bj) { const size_t off = ro + bj * HALF; const u32x4 g = *(const u32x4*)(G + off);
;                     f32x4 v0 = acc[ai][bj][m][0], v1 = acc[ai][bj][m][1];
;                     v0[0] *= bf_lo(g.x); v0[1] *= bf_hi(g.x); v0[2] *= bf_lo(g.y); v0[3] *= bf_hi(g.y); v1[0] *= bf_lo(g.z); v1[1] *= bf_hi(g.z); v1[2] *= bf_lo(g.w); v1[3] *= bf_hi(g.w);
;                     if (MODE == 1) { const u32x4 p = *(const u32x4*)(O + off);
;                         v0[0] += bf_lo(p.x); v0[1] += bf_hi(p.x); v0[2] += bf_lo(p.y); v0[3] += bf_hi(p.y); v1[0] += bf_lo(p.z); v1[1] += bf_hi(p.z); v1[2] += bf_lo(p.w); v1[3] += bf_hi(p.w); }
;                     u32x4 w; w.x = cvt_pk_bf16(v0[0], v0[1]); w.y = cvt_pk_bf16(v0[2], v0[3]); w.z = cvt_pk_bf16(v1[0], v1[1]); w.w = cvt_pk_bf16(v1[2], v1[3]);
;                     *(u32x4*)(O + off) = w; } }
	v_lshlrev_b32_e32 v236, 16, v184
	v_and_b32_e32 v237, 0xffff0000, v184
	v_lshlrev_b32_e32 v238, 16, v185
	v_and_b32_e32 v239, 0xffff0000, v185
	v_lshlrev_b32_e32 v240, 16, v186
	v_and_b32_e32 v241, 0xffff0000, v186
	v_lshlrev_b32_e32 v242, 16, v187
	v_and_b32_e32 v243, 0xffff0000, v187
	v_mul_f32_e32 v44, v44, v236
	v_mul_f32_e32 v45, v45, v237
	v_mul_f32_e32 v46, v46, v238
	v_mul_f32_e32 v47, v47, v239
	v_mul_f32_e32 v40, v40, v240
	v_mul_f32_e32 v41, v41, v241
	v_mul_f32_e32 v42, v42, v242
	v_mul_f32_e32 v43, v43, v243
	v_cvt_pk_bf16_f32 v44, v44, v45
	v_cvt_pk_bf16_f32 v45, v46, v47
	v_cvt_pk_bf16_f32 v46, v40, v41
	v_cvt_pk_bf16_f32 v47, v42, v43
	global_store_dwordx4 v144, v[44:47], s[68:69]
	v_lshlrev_b32_e32 v236, 16, v188
	v_and_b32_e32 v237, 0xffff0000, v188
	v_lshlrev_b32_e32 v238, 16, v189
	v_and_b32_e32 v239, 0xffff0000, v189
	v_lshlrev_b32_e32 v240, 16, v190
	v_and_b32_e32 v241, 0xffff0000, v190
	v_lshlrev_b32_e32 v242, 16, v191
	v_and_b32_e32 v243, 0xffff0000, v191
	v_mul_f32_e32 v36, v36, v236
	v_mul_f32_e32 v37, v37, v237
	v_mul_f32_e32 v38, v38, v238
	v_mul_f32_e32 v39, v39, v239
	v_mul_f32_e32 v32, v32, v240
	v_mul_f32_e32 v33, v33, v241
	v_mul_f32_e32 v34, v34, v242
	v_mul_f32_e32 v35, v35, v243
	v_cvt_pk_bf16_f32 v36, v36, v37
	v_cvt_pk_bf16_f32 v37, v38, v39
	v_cvt_pk_bf16_f32 v38, v32, v33
	v_cvt_pk_bf16_f32 v39, v34, v35
	global_store_dwordx4 v144, v[36:39], s[68:69] offset:256
	s_add_u32 s68, s68, 0x10000
	s_addc_u32 s69, s69, 0
	s_waitcnt vmcnt(8)
	v_lshlrev_b32_e32 v236, 16, v200
	v_and_b32_e32 v237, 0xffff0000, v200
	v_lshlrev_b32_e32 v238, 16, v201
	v_and_b32_e32 v239, 0xffff0000, v201
	v_lshlrev_b32_e32 v240, 16, v202
	v_and_b32_e32 v241, 0xffff0000, v202
	v_lshlrev_b32_e32 v242, 16, v203
	v_and_b32_e32 v243, 0xffff0000, v203
	v_mul_f32_e32 v28, v28, v236
	v_mul_f32_e32 v29, v29, v237
	v_mul_f32_e32 v30, v30, v238
	v_mul_f32_e32 v31, v31, v239
	v_mul_f32_e32 v24, v24, v240
	v_mul_f32_e32 v25, v25, v241
	v_mul_f32_e32 v26, v26, v242
	v_mul_f32_e32 v27, v27, v243
	v_cvt_pk_bf16_f32 v28, v28, v29
	v_cvt_pk_bf16_f32 v29, v30, v31
	v_cvt_pk_bf16_f32 v30, v24, v25
	v_cvt_pk_bf16_f32 v31, v26, v27
	global_store_dwordx4 v144, v[28:31], s[68:69]
	v_lshlrev_b32_e32 v236, 16, v204
	v_and_b32_e32 v237, 0xffff0000, v204
	v_lshlrev_b32_e32 v238, 16, v205
	v_and_b32_e32 v239, 0xffff0000, v205
	v_lshlrev_b32_e32 v240, 16, v206
	v_and_b32_e32 v241, 0xffff0000, v206
	v_lshlrev_b32_e32 v242, 16, v207
	v_and_b32_e32 v243, 0xffff0000, v207
	v_mul_f32_e32 v20, v20, v236
	v_mul_f32_e32 v21, v21, v237
	v_mul_f32_e32 v22, v22, v238
	v_mul_f32_e32 v23, v23, v239
	v_mul_f32_e32 v16, v16, v240
	v_mul_f32_e32 v17, v17, v241
	v_mul_f32_e32 v18, v18, v242
	v_mul_f32_e32 v19, v19, v243
	v_cvt_pk_bf16_f32 v20, v20, v21
	v_cvt_pk_bf16_f32 v21, v22, v23
	v_cvt_pk_bf16_f32 v22, v16, v17
	v_cvt_pk_bf16_f32 v23, v18, v19
	global_store_dwordx4 v144, v[20:23], s[68:69] offset:256
	s_add_u32 s68, s68, 0x10000
	s_addc_u32 s69, s69, 0
	s_waitcnt vmcnt(6)
	v_lshlrev_b32_e32 v236, 16, v216
	v_and_b32_e32 v237, 0xffff0000, v216
	v_lshlrev_b32_e32 v238, 16, v217
	v_and_b32_e32 v239, 0xffff0000, v217
	v_lshlrev_b32_e32 v240, 16, v218
	v_and_b32_e32 v241, 0xffff0000, v218
	v_lshlrev_b32_e32 v242, 16, v219
	v_and_b32_e32 v243, 0xffff0000, v219
	v_mul_f32_e32 v12, v12, v236
	v_mul_f32_e32 v13, v13, v237
	v_mul_f32_e32 v14, v14, v238
	v_mul_f32_e32 v15, v15, v239
	v_mul_f32_e32 v8, v8, v240
	v_mul_f32_e32 v9, v9, v241
	v_mul_f32_e32 v10, v10, v242
	v_mul_f32_e32 v11, v11, v243
	v_cvt_pk_bf16_f32 v12, v12, v13
	v_cvt_pk_bf16_f32 v13, v14, v15
	v_cvt_pk_bf16_f32 v14, v8, v9
	v_cvt_pk_bf16_f32 v15, v10, v11
	global_store_dwordx4 v144, v[12:15], s[68:69]
	v_lshlrev_b32_e32 v236, 16, v220
	v_and_b32_e32 v237, 0xffff0000, v220
	v_lshlrev_b32_e32 v238, 16, v221
	v_and_b32_e32 v239, 0xffff0000, v221
	v_lshlrev_b32_e32 v240, 16, v222
	v_and_b32_e32 v241, 0xffff0000, v222
	v_lshlrev_b32_e32 v242, 16, v223
	v_and_b32_e32 v243, 0xffff0000, v223
	v_mul_f32_e32 v4, v4, v236
	v_mul_f32_e32 v5, v5, v237
	v_mul_f32_e32 v6, v6, v238
	v_mul_f32_e32 v7, v7, v239
	v_mul_f32_e32 v0, v0, v240
	v_mul_f32_e32 v1, v1, v241
	v_mul_f32_e32 v2, v2, v242
	v_mul_f32_e32 v3, v3, v243
	v_cvt_pk_bf16_f32 v4, v4, v5
	v_cvt_pk_bf16_f32 v5, v6, v7
	v_cvt_pk_bf16_f32 v6, v0, v1
	v_cvt_pk_bf16_f32 v7, v2, v3
	global_store_dwordx4 v144, v[4:7], s[68:69] offset:256
	s_nop 1
	s_cbranch_vccnz .LBB0_624
	s_andn2_b64 vcc, exec, s[10:11]
	s_cbranch_vccnz .LBB0_623
	s_barrier
	s_branch .LBB0_623

; __device__ __forceinline__ unsigned cvt_pk_bf16(float lo, float hi) { unsigned r; asm volatile("v_cvt_pk_bf16_f32 %0, %1, %2" : "=v"(r) : "v"(lo), "v"(hi)); return r; }
; __device__ __forceinline__ float bf_lo(unsigned w) { return __uint_as_float(w << 16); }
; __device__ __forceinline__ float bf_hi(unsigned w) { return __uint_as_float(w & 0xffff0000u); }
;     __device__ __forceinline__ void operator()(const f32x4 (&acc)[2][2][4][2], const Unit& u, int wr, int wc, int fr, int fq) const {
;     ...
;             for (int m = 0; m < 4; ++m) { const size_t ro = (size_t)(row0 + ai * HALF + m * 16) * 2048 + col0;
; #pragma unroll
;                 for (int bj = 0; bj < 2; ++bj) { const size_t off = ro + bj * HALF; const u32x4 g = *(const u32x4*)(G + off);
;                     f32x4 v0 = acc[ai][bj][m][0], v1 = acc[ai][bj][m][1];
;                     v0[0] *= bf_lo(g.x); v0[1] *= bf_hi(g.x); v0[2] *= bf_lo(g.y); v0[3] *= bf_hi(g.y); v1[0] *= bf_lo(g.z); v1[1] *= bf_hi(g.z); v1[2] *= bf_lo(g.w); v1[3] *= bf_hi(g.w);
;                     if (MODE == 1) { const u32x4 p = *(const u32x4*)(O + off);
;                         v0[0] += bf_lo(p.x); v0[1] += bf_hi(p.x); v0[2] += bf_lo(p.y); v0[3] += bf_hi(p.y); v1[0] += bf_lo(p.z); v1[1] += bf_hi(p.z); v1[2] += bf_lo(p.w); v1[3] += bf_hi(p.w); }
;                     u32x4 w; w.x = cvt_pk_bf16(v0[0], v0[1]); w.y = cvt_pk_bf16(v0[2], v0[3]); w.z = cvt_pk_bf16(v1[0], v1[1]); w.w = cvt_pk_bf16(v1[2], v1[3]);
;                     *(u32x4*)(O + off) = w; } }
.LBB0_659:
	s_andn2_b64 vcc, exec, s[0:1]
	s_mov_b64 s[0:1], -1
	v_lshlrev_b32_e32 v144, 12, v160
	v_lshl_add_u32 v144, v153, 1, v144
	s_lshl_b32 s72, s2, 20
	s_lshl_b32 s73, s63, 9
	s_add_u32 s72, s72, s73
	s_add_u32 s66, s12, s72
	s_addc_u32 s67, s13, 0
	s_add_u32 s68, s6, s72
	s_addc_u32 s69, s7, 0
	s_add_u32 s70, s6, s72
	s_addc_u32 s71, s7, 0
	global_load_dwordx4 v[168:171], v144, s[66:67]
	global_load_dwordx4 v[172:175], v144, s[66:67] offset:256
	global_load_dwordx4 v[176:179], v144, s[70:71]
	global_load_dwordx4 v[180:183], v144, s[70:71] offset:256
	s_add_u32 s66, s66, 0x10000
	s_addc_u32 s67, s67, 0
	s_add_u32 s70, s70, 0x10000
	s_addc_u32 s71, s71, 0
	global_load_dwordx4 v[184:187], v144, s[66:67]
	global_load_dwordx4 v[188:191], v144, s[66:67] offset:256
	global_load_dwordx4 v[192:195], v144, s[70:71]
	global_load_dwordx4 v[196:199], v144, s[70:71] offset:256
	s_add_u32 s66, s66, 0x10000
	s_addc_u32 s67, s67, 0
	s_add_u32 s70, s70, 0x10000
	s_addc_u32 s71, s71, 0
	global_load_dwordx4 v[200:203], v144, s[66:67]
	global_load_dwordx4 v[204:207], v144, s[66:67] offset:256
	global_load_dwordx4 v[208:211], v144, s[70:71]
	global_load_dwordx4 v[212:215], v144, s[70:71] offset:256
	s_add_u32 s66, s66, 0x10000
	s_addc_u32 s67, s67, 0
	s_add_u32 s70, s70, 0x10000
	s_addc_u32 s71, s71, 0
	global_load_dwordx4 v[216:219], v144, s[66:67]
	global_load_dwordx4 v[220:223], v144, s[66:67] offset:256
	global_load_dwordx4 v[224:227], v144, s[70:71]
	global_load_dwordx4 v[228:231], v144, s[70:71] offset:256
	s_add_u32 s66, s66, 0x50000
	s_addc_u32 s67, s67, 0
	s_add_u32 s70, s70, 0x50000
	s_addc_u32 s71, s71, 0
	s_waitcnt vmcnt(12)
	v_lshlrev_b32_e32 v236, 16, v168
	v_and_b32_e32 v237, 0xffff0000, v168
	v_lshlrev_b32_e32 v238, 16, v169
	v_and_b32_e32 v239, 0xffff0000, v169
	v_lshlrev_b32_e32 v240, 16, v170
	v_and_b32_e32 v241, 0xffff0000, v170
	v_lshlrev_b32_e32 v242, 16, v171
	v_and_b32_e32 v243, 0xffff0000, v171
	v_lshlrev_b32_e32 v244, 16, v176
	v_and_b32_e32 v245, 0xffff0000, v176
	v_lshlrev_b32_e32 v246, 16, v177
	v_and_b32_e32 v247, 0xffff0000, v177
	v_lshlrev_b32_e32 v248, 16, v178
	v_and_b32_e32 v249, 0xffff0000, v178
	v_lshlrev_b32_e32 v250, 16, v179
	v_and_b32_e32 v251, 0xffff0000, v179
	v_fma_f32 v124, v124, v236, v244
	v_fma_f32 v125, v125, v237, v245
	v_fma_f32 v126, v126, v238, v246
	v_fma_f32 v127, v127, v239, v247
	v_fma_f32 v120, v120, v240, v248
	v_fma_f32 v121, v121, v241, v249
	v_fma_f32 v122, v122, v242, v250
	v_fma_f32 v123, v123, v243, v251
	v_cvt_pk_bf16_f32 v124, v124, v125
	v_cvt_pk_bf16_f32 v125, v126, v127
	v_cvt_pk_bf16_f32 v126, v120, v121
	v_cvt_pk_bf16_f32 v127, v122, v123
	global_store_dwordx4 v144, v[124:127], s[68:69]
	v_lshlrev_b32_e32 v236, 16, v172
	v_and_b32_e32 v237, 0xffff0000, v172
	v_lshlrev_b32_e32 v238, 16, v173
	v_and_b32_e32 v239, 0xffff0000, v173
	v_lshlrev_b32_e32 v240, 16, v174
	v_and_b32_e32 v241, 0xffff0000, v174
	v_lshlrev_b32_e32 v242, 16, v175
	v_and_b32_e32 v243, 0xffff0000, v175
	v_lshlrev_b32_e32 v244, 16, v180
	v_and_b32_e32 v245, 0xffff0000, v180
	v_lshlrev_b32_e32 v246, 16, v181
	v_and_b32_e32 v247, 0xffff0000, v181
	v_lshlrev_b32_e32 v248, 16, v182
	v_and_b32_e32 v249, 0xffff0000, v182
	v_lshlrev_b32_e32 v250, 16, v183
	v_and_b32_e32 v251, 0xffff0000, v183
	v_fma_f32 v116, v116, v236, v244
	v_fma_f32 v117, v117, v237, v245
	v_fma_f32 v118, v118, v238, v246
	v_fma_f32 v119, v119, v239, v247
	v_fma_f32 v112, v112, v240, v248
	v_fma_f32 v113, v113, v241, v249
	v_fma_f32 v114, v114, v242, v250
	v_fma_f32 v115, v115, v243, v251
	v_cvt_pk_bf16_f32 v116, v116, v117
	v_cvt_pk_bf16_f32 v117, v118, v119
	v_cvt_pk_bf16_f32 v118, v112, v113
	v_cvt_pk_bf16_f32 v119, v114, v115
	global_store_dwordx4 v144, v[116:119], s[68:69] offset:256
	s_add_u32 s68, s68, 0x10000
	s_addc_u32 s69, s69, 0
	global_load_dwordx4 v[168:171], v144, s[66:67]
	global_load_dwordx4 v[172:175], v144, s[66:67] offset:256
	global_load_dwordx4 v[176:179], v144, s[70:71]
	global_load_dwordx4 v[180:183], v144, s[70:71] offset:256
	s_add_u32 s66, s66, 0x10000
	s_addc_u32 s67, s67, 0
	s_add_u32 s70, s70, 0x10000
	s_addc_u32 s71, s71, 0
	s_waitcnt vmcnt(14)
	v_lshlrev_b32_e32 v236, 16, v184
	v_and_b32_e32 v237, 0xffff0000, v184
	v_lshlrev_b32_e32 v238, 16, v185
	v_and_b32_e32 v239, 0xffff0000, v185
	v_lshlrev_b32_e32 v240, 16, v186
	v_and_b32_e32 v241, 0xffff0000, v186
	v_lshlrev_b32_e32 v242, 16, v187
	v_and_b32_e32 v243, 0xffff0000, v187
	v_lshlrev_b32_e32 v244, 16, v192
	v_and_b32_e32 v245, 0xffff0000, v192
	v_lshlrev_b32_e32 v246, 16, v193
	v_and_b32_e32 v247, 0xffff0000, v193
	v_lshlrev_b32_e32 v248, 16, v194
	v_and_b32_e32 v249, 0xffff0000, v194
	v_lshlrev_b32_e32 v250, 16, v195
	v_and_b32_e32 v251, 0xffff0000, v195
	v_fma_f32 v108, v108, v236, v244
	v_fma_f32 v109, v109, v237, v245
	v_fma_f32 v110, v110, v238, v246
	v_fma_f32 v111, v111, v239, v247
	v_fma_f32 v104, v104, v240, v248
	v_fma_f32 v105, v105, v241, v249
	v_fma_f32 v106, v106, v242, v250
	v_fma_f32 v107, v107, v243, v251
	v_cvt_pk_bf16_f32 v108, v108, v109
	v_cvt_pk_bf16_f32 v109, v110, v111
	v_cvt_pk_bf16_f32 v110, v104, v105
	v_cvt_pk_bf16_f32 v111, v106, v107
	global_store_dwordx4 v144, v[108:111], s[68:69]
	v_lshlrev_b32_e32 v236, 16, v188
	v_and_b32_e32 v237, 0xffff0000, v188
	v_lshlrev_b32_e32 v238, 16, v189
	v_and_b32_e32 v239, 0xffff0000, v189
	v_lshlrev_b32_e32 v240, 16, v190
	v_and_b32_e32 v241, 0xffff0000, v190
	v_lshlrev_b32_e32 v242, 16, v191
	v_and_b32_e32 v243, 0xffff0000, v191
	v_lshlrev_b32_e32 v244, 16, v196
	v_and_b32_e32 v245, 0xffff0000, v196
	v_lshlrev_b32_e32 v246, 16, v197
	v_and_b32_e32 v247, 0xffff0000, v197
	v_lshlrev_b32_e32 v248, 16, v198
	v_and_b32_e32 v249, 0xffff0000, v198
	v_lshlrev_b32_e32 v250, 16, v199
	v_and_b32_e32 v251, 0xffff0000, v199
	v_fma_f32 v100, v100, v236, v244
	v_fma_f32 v101, v101, v237, v245
	v_fma_f32 v102, v102, v238, v246
	v_fma_f32 v103, v103, v239, v247
	v_fma_f32 v96, v96, v240, v248
	v_fma_f32 v97, v97, v241, v249
	v_fma_f32 v98, v98, v242, v250
	v_fma_f32 v99, v99, v243, v251
	v_cvt_pk_bf16_f32 v100, v100, v101
	v_cvt_pk_bf16_f32 v101, v102, v103
	v_cvt_pk_bf16_f32 v102, v96, v97
	v_cvt_pk_bf16_f32 v103, v98, v99
	global_store_dwordx4 v144, v[100:103], s[68:69] offset:256
	s_add_u32 s68, s68, 0x10000
	s_addc_u32 s69, s69, 0
	global_load_dwordx4 v[184:187], v144, s[66:67]
	global_load_dwordx4 v[188:191], v144, s[66:67] offset:256
	global_load_dwordx4 v[192:195], v144, s[70:71]
	global_load_dwordx4 v[196:199], v144, s[70:71] offset:256
	s_add_u32 s66, s66, 0x10000
	s_addc_u32 s67, s67, 0
	s_add_u32 s70, s70, 0x10000
	s_addc_u32 s71, s71, 0
	s_waitcnt vmcnt(16)
; __device__ __forceinline__ unsigned cvt_pk_bf16(float lo, float hi) { unsigned r; asm volatile("v_cvt_pk_bf16_f32 %0, %1, %2" : "=v"(r) : "v"(lo), "v"(hi)); return r; }
; __device__ __forceinline__ float bf_lo(unsigned w) { return __uint_as_float(w << 16); }
; __device__ __forceinline__ float bf_hi(unsigned w) { return __uint_as_float(w & 0xffff0000u); }
;     __device__ __forceinline__ void operator()(const f32x4 (&acc)[2][2][4][2], const Unit& u, int wr, int wc, int fr, int fq) const {
;     ...
;             for (int m = 0; m < 4; ++m) { const size_t ro = (size_t)(row0 + ai * HALF + m * 16) * 2048 + col0;
; #pragma unroll
;                 for (int bj = 0; bj < 2; ++bj) { const size_t off = ro + bj * HALF; const u32x4 g = *(const u32x4*)(G + off);
;                     f32x4 v0 = acc[ai][bj][m][0], v1 = acc[ai][bj][m][1];
;                     v0[0] *= bf_lo(g.x); v0[1] *= bf_hi(g.x); v0[2] *= bf_lo(g.y); v0[3] *= bf_hi(g.y); v1[0] *= bf_lo(g.z); v1[1] *= bf_hi(g.z); v1[2] *= bf_lo(g.w); v1[3] *= bf_hi(g.w);
;                     if (MODE == 1) { const u32x4 p = *(const u32x4*)(O + off);
;                         v0[0] += bf_lo(p.x); v0[1] += bf_hi(p.x); v0[2] += bf_lo(p.y); v0[3] += bf_hi(p.y); v1[0] += bf_lo(p.z); v1[1] += bf_hi(p.z); v1[2] += bf_lo(p.w); v1[3] += bf_hi(p.w); }
;                     u32x4 w; w.x = cvt_pk_bf16(v0[0], v0[1]); w.y = cvt_pk_bf16(v0[2], v0[3]); w.z = cvt_pk_bf16(v1[0], v1[1]); w.w = cvt_pk_bf16(v1[2], v1[3]);
;                     *(u32x4*)(O + off) = w; } }
	v_lshlrev_b32_e32 v236, 16, v200
	v_and_b32_e32 v237, 0xffff0000, v200
	v_lshlrev_b32_e32 v238, 16, v201
	v_and_b32_e32 v239, 0xffff0000, v201
	v_lshlrev_b32_e32 v240, 16, v202
	v_and_b32_e32 v241, 0xffff0000, v202
	v_lshlrev_b32_e32 v242, 16, v203
	v_and_b32_e32 v243, 0xffff0000, v203
	v_lshlrev_b32_e32 v244, 16, v208
	v_and_b32_e32 v245, 0xffff0000, v208
	v_lshlrev_b32_e32 v246, 16, v209
	v_and_b32_e32 v247, 0xffff0000, v209
	v_lshlrev_b32_e32 v248, 16, v210
	v_and_b32_e32 v249, 0xffff0000, v210
	v_lshlrev_b32_e32 v250, 16, v211
	v_and_b32_e32 v251, 0xffff0000, v211
	v_fma_f32 v92, v92, v236, v244
	v_fma_f32 v93, v93, v237, v245
	v_fma_f32 v94, v94, v238, v246
	v_fma_f32 v95, v95, v239, v247
	v_fma_f32 v88, v88, v240, v248
	v_fma_f32 v89, v89, v241, v249
	v_fma_f32 v90, v90, v242, v250
	v_fma_f32 v91, v91, v243, v251
	v_cvt_pk_bf16_f32 v92, v92, v93
	v_cvt_pk_bf16_f32 v93, v94, v95
	v_cvt_pk_bf16_f32 v94, v88, v89
	v_cvt_pk_bf16_f32 v95, v90, v91
	global_store_dwordx4 v144, v[92:95], s[68:69]
	v_lshlrev_b32_e32 v236, 16, v204
	v_and_b32_e32 v237, 0xffff0000, v204
	v_lshlrev_b32_e32 v238, 16, v205
	v_and_b32_e32 v239, 0xffff0000, v205
	v_lshlrev_b32_e32 v240, 16, v206
	v_and_b32_e32 v241, 0xffff0000, v206
	v_lshlrev_b32_e32 v242, 16, v207
	v_and_b32_e32 v243, 0xffff0000, v207
	v_lshlrev_b32_e32 v244, 16, v212
	v_and_b32_e32 v245, 0xffff0000, v212
	v_lshlrev_b32_e32 v246, 16, v213
	v_and_b32_e32 v247, 0xffff0000, v213
	v_lshlrev_b32_e32 v248, 16, v214
	v_and_b32_e32 v249, 0xffff0000, v214
	v_lshlrev_b32_e32 v250, 16, v215
	v_and_b32_e32 v251, 0xffff0000, v215
	v_fma_f32 v84, v84, v236, v244
	v_fma_f32 v85, v85, v237, v245
	v_fma_f32 v86, v86, v238, v246
	v_fma_f32 v87, v87, v239, v247
	v_fma_f32 v80, v80, v240, v248
	v_fma_f32 v81, v81, v241, v249
	v_fma_f32 v82, v82, v242, v250
	v_fma_f32 v83, v83, v243, v251
	v_cvt_pk_bf16_f32 v84, v84, v85
	v_cvt_pk_bf16_f32 v85, v86, v87
	v_cvt_pk_bf16_f32 v86, v80, v81
	v_cvt_pk_bf16_f32 v87, v82, v83
	global_store_dwordx4 v144, v[84:87], s[68:69] offset:256
	s_add_u32 s68, s68, 0x10000
	s_addc_u32 s69, s69, 0
	global_load_dwordx4 v[200:203], v144, s[66:67]
	global_load_dwordx4 v[204:207], v144, s[66:67] offset:256
	global_load_dwordx4 v[208:211], v144, s[70:71]
	global_load_dwordx4 v[212:215], v144, s[70:71] offset:256
	s_add_u32 s66, s66, 0x10000
	s_addc_u32 s67, s67, 0
	s_add_u32 s70, s70, 0x10000
	s_addc_u32 s71, s71, 0
	s_waitcnt vmcnt(18)
	v_lshlrev_b32_e32 v236, 16, v216
	v_and_b32_e32 v237, 0xffff0000, v216
	v_lshlrev_b32_e32 v238, 16, v217
	v_and_b32_e32 v239, 0xffff0000, v217
	v_lshlrev_b32_e32 v240, 16, v218
	v_and_b32_e32 v241, 0xffff0000, v218
	v_lshlrev_b32_e32 v242, 16, v219
	v_and_b32_e32 v243, 0xffff0000, v219
	v_lshlrev_b32_e32 v244, 16, v224
	v_and_b32_e32 v245, 0xffff0000, v224
	v_lshlrev_b32_e32 v246, 16, v225
	v_and_b32_e32 v247, 0xffff0000, v225
	v_lshlrev_b32_e32 v248, 16, v226
	v_and_b32_e32 v249, 0xffff0000, v226
	v_lshlrev_b32_e32 v250, 16, v227
	v_and_b32_e32 v251, 0xffff0000, v227
	v_fma_f32 v76, v76, v236, v244
	v_fma_f32 v77, v77, v237, v245
	v_fma_f32 v78, v78, v238, v246
	v_fma_f32 v79, v79, v239, v247
	v_fma_f32 v72, v72, v240, v248
	v_fma_f32 v73, v73, v241, v249
	v_fma_f32 v74, v74, v242, v250
	v_fma_f32 v75, v75, v243, v251
	v_cvt_pk_bf16_f32 v76, v76, v77
	v_cvt_pk_bf16_f32 v77, v78, v79
	v_cvt_pk_bf16_f32 v78, v72, v73
	v_cvt_pk_bf16_f32 v79, v74, v75
	global_store_dwordx4 v144, v[76:79], s[68:69]
	v_lshlrev_b32_e32 v236, 16, v220
	v_and_b32_e32 v237, 0xffff0000, v220
	v_lshlrev_b32_e32 v238, 16, v221
	v_and_b32_e32 v239, 0xffff0000, v221
	v_lshlrev_b32_e32 v240, 16, v222
	v_and_b32_e32 v241, 0xffff0000, v222
	v_lshlrev_b32_e32 v242, 16, v223
	v_and_b32_e32 v243, 0xffff0000, v223
	v_lshlrev_b32_e32 v244, 16, v228
	v_and_b32_e32 v245, 0xffff0000, v228
	v_lshlrev_b32_e32 v246, 16, v229
	v_and_b32_e32 v247, 0xffff0000, v229
	v_lshlrev_b32_e32 v248, 16, v230
	v_and_b32_e32 v249, 0xffff0000, v230
	v_lshlrev_b32_e32 v250, 16, v231
	v_and_b32_e32 v251, 0xffff0000, v231
	v_fma_f32 v68, v68, v236, v244
	v_fma_f32 v69, v69, v237, v245
	v_fma_f32 v70, v70, v238, v246
	v_fma_f32 v71, v71, v239, v247
	v_fma_f32 v64, v64, v240, v248
	v_fma_f32 v65, v65, v241, v249
	v_fma_f32 v66, v66, v242, v250
	v_fma_f32 v67, v67, v243, v251
	v_cvt_pk_bf16_f32 v68, v68, v69
	v_cvt_pk_bf16_f32 v69, v70, v71
	v_cvt_pk_bf16_f32 v70, v64, v65
	v_cvt_pk_bf16_f32 v71, v66, v67
	global_store_dwordx4 v144, v[68:71], s[68:69] offset:256
	s_add_u32 s68, s68, 0x50000
	s_addc_u32 s69, s69, 0
	global_load_dwordx4 v[216:219], v144, s[66:67]
	global_load_dwordx4 v[220:223], v144, s[66:67] offset:256
	global_load_dwordx4 v[224:227], v144, s[70:71]
	global_load_dwordx4 v[228:231], v144, s[70:71] offset:256
	s_waitcnt vmcnt(18)
; __device__ __forceinline__ unsigned cvt_pk_bf16(float lo, float hi) { unsigned r; asm volatile("v_cvt_pk_bf16_f32 %0, %1, %2" : "=v"(r) : "v"(lo), "v"(hi)); return r; }
; __device__ __forceinline__ float bf_lo(unsigned w) { return __uint_as_float(w << 16); }
; __device__ __forceinline__ float bf_hi(unsigned w) { return __uint_as_float(w & 0xffff0000u); }
;     __device__ __forceinline__ void operator()(const f32x4 (&acc)[2][2][4][2], const Unit& u, int wr, int wc, int fr, int fq) const {
;     ...
;             for (int m = 0; m < 4; ++m) { const size_t ro = (size_t)(row0 + ai * HALF + m * 16) * 2048 + col0;
; #pragma unroll
;                 for (int bj = 0; bj < 2; ++bj) { const size_t off = ro + bj * HALF; const u32x4 g = *(const u32x4*)(G + off);
;                     f32x4 v0 = acc[ai][bj][m][0], v1 = acc[ai][bj][m][1];
;                     v0[0] *= bf_lo(g.x); v0[1] *= bf_hi(g.x); v0[2] *= bf_lo(g.y); v0[3] *= bf_hi(g.y); v1[0] *= bf_lo(g.z); v1[1] *= bf_hi(g.z); v1[2] *= bf_lo(g.w); v1[3] *= bf_hi(g.w);
;                     if (MODE == 1) { const u32x4 p = *(const u32x4*)(O + off);
;                         v0[0] += bf_lo(p.x); v0[1] += bf_hi(p.x); v0[2] += bf_lo(p.y); v0[3] += bf_hi(p.y); v1[0] += bf_lo(p.z); v1[1] += bf_hi(p.z); v1[2] += bf_lo(p.w); v1[3] += bf_hi(p.w); }
;                     u32x4 w; w.x = cvt_pk_bf16(v0[0], v0[1]); w.y = cvt_pk_bf16(v0[2], v0[3]); w.z = cvt_pk_bf16(v1[0], v1[1]); w.w = cvt_pk_bf16(v1[2], v1[3]);
;                     *(u32x4*)(O + off) = w; } }
	v_lshlrev_b32_e32 v236, 16, v168
	v_and_b32_e32 v237, 0xffff0000, v168
	v_lshlrev_b32_e32 v238, 16, v169
	v_and_b32_e32 v239, 0xffff0000, v169
	v_lshlrev_b32_e32 v240, 16, v170
	v_and_b32_e32 v241, 0xffff0000, v170
	v_lshlrev_b32_e32 v242, 16, v171
	v_and_b32_e32 v243, 0xffff0000, v171
	v_lshlrev_b32_e32 v244, 16, v176
	v_and_b32_e32 v245, 0xffff0000, v176
	v_lshlrev_b32_e32 v246, 16, v177
	v_and_b32_e32 v247, 0xffff0000, v177
	v_lshlrev_b32_e32 v248, 16, v178
	v_and_b32_e32 v249, 0xffff0000, v178
	v_lshlrev_b32_e32 v250, 16, v179
	v_and_b32_e32 v251, 0xffff0000, v179
	v_fma_f32 v60, v60, v236, v244
	v_fma_f32 v61, v61, v237, v245
	v_fma_f32 v62, v62, v238, v246
	v_fma_f32 v63, v63, v239, v247
	v_fma_f32 v56, v56, v240, v248
	v_fma_f32 v57, v57, v241, v249
	v_fma_f32 v58, v58, v242, v250
	v_fma_f32 v59, v59, v243, v251
	v_cvt_pk_bf16_f32 v60, v60, v61
	v_cvt_pk_bf16_f32 v61, v62, v63
	v_cvt_pk_bf16_f32 v62, v56, v57
	v_cvt_pk_bf16_f32 v63, v58, v59
	global_store_dwordx4 v144, v[60:63], s[68:69]
	v_lshlrev_b32_e32 v236, 16, v172
	v_and_b32_e32 v237, 0xffff0000, v172
	v_lshlrev_b32_e32 v238, 16, v173
	v_and_b32_e32 v239, 0xffff0000, v173
	v_lshlrev_b32_e32 v240, 16, v174
	v_and_b32_e32 v241, 0xffff0000, v174
	v_lshlrev_b32_e32 v242, 16, v175
	v_and_b32_e32 v243, 0xffff0000, v175
	v_lshlrev_b32_e32 v244, 16, v180
	v_and_b32_e32 v245, 0xffff0000, v180
	v_lshlrev_b32_e32 v246, 16, v181
	v_and_b32_e32 v247, 0xffff0000, v181
	v_lshlrev_b32_e32 v248, 16, v182
	v_and_b32_e32 v249, 0xffff0000, v182
	v_lshlrev_b32_e32 v250, 16, v183
	v_and_b32_e32 v251, 0xffff0000, v183
	v_fma_f32 v52, v52, v236, v244
	v_fma_f32 v53, v53, v237, v245
	v_fma_f32 v54, v54, v238, v246
	v_fma_f32 v55, v55, v239, v247
	v_fma_f32 v48, v48, v240, v248
	v_fma_f32 v49, v49, v241, v249
	v_fma_f32 v50, v50, v242, v250
	v_fma_f32 v51, v51, v243, v251
	v_cvt_pk_bf16_f32 v52, v52, v53
	v_cvt_pk_bf16_f32 v53, v54, v55
	v_cvt_pk_bf16_f32 v54, v48, v49
	v_cvt_pk_bf16_f32 v55, v50, v51
	global_store_dwordx4 v144, v[52:55], s[68:69] offset:256
	s_add_u32 s68, s68, 0x10000
	s_addc_u32 s69, s69, 0
	s_waitcnt vmcnt(14)
	v_lshlrev_b32_e32 v236, 16, v184
	v_and_b32_e32 v237, 0xffff0000, v184
	v_lshlrev_b32_e32 v238, 16, v185
	v_and_b32_e32 v239, 0xffff0000, v185
	v_lshlrev_b32_e32 v240, 16, v186
	v_and_b32_e32 v241, 0xffff0000, v186
	v_lshlrev_b32_e32 v242, 16, v187
	v_and_b32_e32 v243, 0xffff0000, v187
	v_lshlrev_b32_e32 v244, 16, v192
	v_and_b32_e32 v245, 0xffff0000, v192
	v_lshlrev_b32_e32 v246, 16, v193
	v_and_b32_e32 v247, 0xffff0000, v193
	v_lshlrev_b32_e32 v248, 16, v194
	v_and_b32_e32 v249, 0xffff0000, v194
	v_lshlrev_b32_e32 v250, 16, v195
	v_and_b32_e32 v251, 0xffff0000, v195
	v_fma_f32 v44, v44, v236, v244
	v_fma_f32 v45, v45, v237, v245
	v_fma_f32 v46, v46, v238, v246
	v_fma_f32 v47, v47, v239, v247
	v_fma_f32 v40, v40, v240, v248
	v_fma_f32 v41, v41, v241, v249
	v_fma_f32 v42, v42, v242, v250
	v_fma_f32 v43, v43, v243, v251
	v_cvt_pk_bf16_f32 v44, v44, v45
	v_cvt_pk_bf16_f32 v45, v46, v47
	v_cvt_pk_bf16_f32 v46, v40, v41
	v_cvt_pk_bf16_f32 v47, v42, v43
	global_store_dwordx4 v144, v[44:47], s[68:69]
	v_lshlrev_b32_e32 v236, 16, v188
	v_and_b32_e32 v237, 0xffff0000, v188
	v_lshlrev_b32_e32 v238, 16, v189
	v_and_b32_e32 v239, 0xffff0000, v189
	v_lshlrev_b32_e32 v240, 16, v190
	v_and_b32_e32 v241, 0xffff0000, v190
	v_lshlrev_b32_e32 v242, 16, v191
	v_and_b32_e32 v243, 0xffff0000, v191
	v_lshlrev_b32_e32 v244, 16, v196
	v_and_b32_e32 v245, 0xffff0000, v196
	v_lshlrev_b32_e32 v246, 16, v197
	v_and_b32_e32 v247, 0xffff0000, v197
	v_lshlrev_b32_e32 v248, 16, v198
	v_and_b32_e32 v249, 0xffff0000, v198
	v_lshlrev_b32_e32 v250, 16, v199
	v_and_b32_e32 v251, 0xffff0000, v199
	v_fma_f32 v36, v36, v236, v244
	v_fma_f32 v37, v37, v237, v245
	v_fma_f32 v38, v38, v238, v246
	v_fma_f32 v39, v39, v239, v247
	v_fma_f32 v32, v32, v240, v248
	v_fma_f32 v33, v33, v241, v249
	v_fma_f32 v34, v34, v242, v250
	v_fma_f32 v35, v35, v243, v251
	v_cvt_pk_bf16_f32 v36, v36, v37
	v_cvt_pk_bf16_f32 v37, v38, v39
	v_cvt_pk_bf16_f32 v38, v32, v33
	v_cvt_pk_bf16_f32 v39, v34, v35
	global_store_dwordx4 v144, v[36:39], s[68:69] offset:256
	s_add_u32 s68, s68, 0x10000
	s_addc_u32 s69, s69, 0
	s_waitcnt vmcnt(10)
; __device__ __forceinline__ unsigned cvt_pk_bf16(float lo, float hi) { unsigned r; asm volatile("v_cvt_pk_bf16_f32 %0, %1, %2" : "=v"(r) : "v"(lo), "v"(hi)); return r; }
; __device__ __forceinline__ float bf_lo(unsigned w) { return __uint_as_float(w << 16); }
; __device__ __forceinline__ float bf_hi(unsigned w) { return __uint_as_float(w & 0xffff0000u); }
;     __device__ __forceinline__ void operator()(const f32x4 (&acc)[2][2][4][2], const Unit& u, int wr, int wc, int fr, int fq) const {
;     ...
;             for (int m = 0; m < 4; ++m) { const size_t ro = (size_t)(row0 + ai * HALF + m * 16) * 2048 + col0;
; #pragma unroll
;                 for (int bj = 0; bj < 2; ++bj) { const size_t off = ro + bj * HALF; const u32x4 g = *(const u32x4*)(G + off);
;                     f32x4 v0 = acc[ai][bj][m][0], v1 = acc[ai][bj][m][1];
;                     v0[0] *= bf_lo(g.x); v0[1] *= bf_hi(g.x); v0[2] *= bf_lo(g.y); v0[3] *= bf_hi(g.y); v1[0] *= bf_lo(g.z); v1[1] *= bf_hi(g.z); v1[2] *= bf_lo(g.w); v1[3] *= bf_hi(g.w);
;                     if (MODE == 1) { const u32x4 p = *(const u32x4*)(O + off);
;                         v0[0] += bf_lo(p.x); v0[1] += bf_hi(p.x); v0[2] += bf_lo(p.y); v0[3] += bf_hi(p.y); v1[0] += bf_lo(p.z); v1[1] += bf_hi(p.z); v1[2] += bf_lo(p.w); v1[3] += bf_hi(p.w); }
;                     u32x4 w; w.x = cvt_pk_bf16(v0[0], v0[1]); w.y = cvt_pk_bf16(v0[2], v0[3]); w.z = cvt_pk_bf16(v1[0], v1[1]); w.w = cvt_pk_bf16(v1[2], v1[3]);
;                     *(u32x4*)(O + off) = w; } }
	v_lshlrev_b32_e32 v236, 16, v200
	v_and_b32_e32 v237, 0xffff0000, v200
	v_lshlrev_b32_e32 v238, 16, v201
	v_and_b32_e32 v239, 0xffff0000, v201
	v_lshlrev_b32_e32 v240, 16, v202
	v_and_b32_e32 v241, 0xffff0000, v202
	v_lshlrev_b32_e32 v242, 16, v203
	v_and_b32_e32 v243, 0xffff0000, v203
	v_lshlrev_b32_e32 v244, 16, v208
	v_and_b32_e32 v245, 0xffff0000, v208
	v_lshlrev_b32_e32 v246, 16, v209
	v_and_b32_e32 v247, 0xffff0000, v209
	v_lshlrev_b32_e32 v248, 16, v210
	v_and_b32_e32 v249, 0xffff0000, v210
	v_lshlrev_b32_e32 v250, 16, v211
	v_and_b32_e32 v251, 0xffff0000, v211
	v_fma_f32 v28, v28, v236, v244
	v_fma_f32 v29, v29, v237, v245
	v_fma_f32 v30, v30, v238, v246
	v_fma_f32 v31, v31, v239, v247
	v_fma_f32 v24, v24, v240, v248
	v_fma_f32 v25, v25, v241, v249
	v_fma_f32 v26, v26, v242, v250
	v_fma_f32 v27, v27, v243, v251
	v_cvt_pk_bf16_f32 v28, v28, v29
	v_cvt_pk_bf16_f32 v29, v30, v31
	v_cvt_pk_bf16_f32 v30, v24, v25
	v_cvt_pk_bf16_f32 v31, v26, v27
	global_store_dwordx4 v144, v[28:31], s[68:69]
	v_lshlrev_b32_e32 v236, 16, v204
	v_and_b32_e32 v237, 0xffff0000, v204
	v_lshlrev_b32_e32 v238, 16, v205
	v_and_b32_e32 v239, 0xffff0000, v205
	v_lshlrev_b32_e32 v240, 16, v206
	v_and_b32_e32 v241, 0xffff0000, v206
	v_lshlrev_b32_e32 v242, 16, v207
	v_and_b32_e32 v243, 0xffff0000, v207
	v_lshlrev_b32_e32 v244, 16, v212
	v_and_b32_e32 v245, 0xffff0000, v212
	v_lshlrev_b32_e32 v246, 16, v213
	v_and_b32_e32 v247, 0xffff0000, v213
	v_lshlrev_b32_e32 v248, 16, v214
	v_and_b32_e32 v249, 0xffff0000, v214
	v_lshlrev_b32_e32 v250, 16, v215
	v_and_b32_e32 v251, 0xffff0000, v215
	v_fma_f32 v20, v20, v236, v244
	v_fma_f32 v21, v21, v237, v245
	v_fma_f32 v22, v22, v238, v246
	v_fma_f32 v23, v23, v239, v247
	v_fma_f32 v16, v16, v240, v248
	v_fma_f32 v17, v17, v241, v249
	v_fma_f32 v18, v18, v242, v250
	v_fma_f32 v19, v19, v243, v251
	v_cvt_pk_bf16_f32 v20, v20, v21
	v_cvt_pk_bf16_f32 v21, v22, v23
	v_cvt_pk_bf16_f32 v22, v16, v17
	v_cvt_pk_bf16_f32 v23, v18, v19
	global_store_dwordx4 v144, v[20:23], s[68:69] offset:256
	s_add_u32 s68, s68, 0x10000
	s_addc_u32 s69, s69, 0
	s_waitcnt vmcnt(6)
	v_lshlrev_b32_e32 v236, 16, v216
	v_and_b32_e32 v237, 0xffff0000, v216
	v_lshlrev_b32_e32 v238, 16, v217
	v_and_b32_e32 v239, 0xffff0000, v217
	v_lshlrev_b32_e32 v240, 16, v218
	v_and_b32_e32 v241, 0xffff0000, v218
	v_lshlrev_b32_e32 v242, 16, v219
	v_and_b32_e32 v243, 0xffff0000, v219
	v_lshlrev_b32_e32 v244, 16, v224
	v_and_b32_e32 v245, 0xffff0000, v224
	v_lshlrev_b32_e32 v246, 16, v225
	v_and_b32_e32 v247, 0xffff0000, v225
	v_lshlrev_b32_e32 v248, 16, v226
	v_and_b32_e32 v249, 0xffff0000, v226
	v_lshlrev_b32_e32 v250, 16, v227
	v_and_b32_e32 v251, 0xffff0000, v227
	v_fma_f32 v12, v12, v236, v244
	v_fma_f32 v13, v13, v237, v245
	v_fma_f32 v14, v14, v238, v246
	v_fma_f32 v15, v15, v239, v247
	v_fma_f32 v8, v8, v240, v248
	v_fma_f32 v9, v9, v241, v249
	v_fma_f32 v10, v10, v242, v250
	v_fma_f32 v11, v11, v243, v251
	v_cvt_pk_bf16_f32 v12, v12, v13
	v_cvt_pk_bf16_f32 v13, v14, v15
	v_cvt_pk_bf16_f32 v14, v8, v9
	v_cvt_pk_bf16_f32 v15, v10, v11
	global_store_dwordx4 v144, v[12:15], s[68:69]
	v_lshlrev_b32_e32 v236, 16, v220
	v_and_b32_e32 v237, 0xffff0000, v220
	v_lshlrev_b32_e32 v238, 16, v221
	v_and_b32_e32 v239, 0xffff0000, v221
	v_lshlrev_b32_e32 v240, 16, v222
	v_and_b32_e32 v241, 0xffff0000, v222
	v_lshlrev_b32_e32 v242, 16, v223
	v_and_b32_e32 v243, 0xffff0000, v223
	v_lshlrev_b32_e32 v244, 16, v228
	v_and_b32_e32 v245, 0xffff0000, v228
	v_lshlrev_b32_e32 v246, 16, v229
	v_and_b32_e32 v247, 0xffff0000, v229
	v_lshlrev_b32_e32 v248, 16, v230
	v_and_b32_e32 v249, 0xffff0000, v230
	v_lshlrev_b32_e32 v250, 16, v231
	v_and_b32_e32 v251, 0xffff0000, v231
	v_fma_f32 v4, v4, v236, v244
	v_fma_f32 v5, v5, v237, v245
	v_fma_f32 v6, v6, v238, v246
	v_fma_f32 v7, v7, v239, v247
	v_fma_f32 v0, v0, v240, v248
	v_fma_f32 v1, v1, v241, v249
	v_fma_f32 v2, v2, v242, v250
	v_fma_f32 v3, v3, v243, v251
	v_cvt_pk_bf16_f32 v4, v4, v5
	v_cvt_pk_bf16_f32 v5, v6, v7
	v_cvt_pk_bf16_f32 v6, v0, v1
	v_cvt_pk_bf16_f32 v7, v2, v3
	global_store_dwordx4 v144, v[4:7], s[68:69] offset:256
	s_nop 1
	s_cbranch_vccnz .LBB0_648
	s_andn2_b64 vcc, exec, s[10:11]
	s_cbranch_vccnz .LBB0_647
	s_barrier
	s_branch .LBB0_647

; __global__ void __launch_bounds__(NWAVES * 64, 2) mega(Args args) {
	.amdhsa_kernel _Z4mega4Args
		.amdhsa_group_segment_fixed_size 0
		.amdhsa_private_segment_fixed_size 0
		.amdhsa_kernarg_size 416
		.amdhsa_user_sgpr_count 2
		.amdhsa_user_sgpr_dispatch_ptr 0
		.amdhsa_user_sgpr_queue_ptr 0
		.amdhsa_user_sgpr_kernarg_segment_ptr 1
		.amdhsa_user_sgpr_dispatch_id 0
		.amdhsa_user_sgpr_kernarg_preload_length 0
		.amdhsa_user_sgpr_kernarg_preload_offset 0
		.amdhsa_user_sgpr_private_segment_size 0
		.amdhsa_uses_dynamic_stack 0
		.amdhsa_enable_private_segment 0
		.amdhsa_system_sgpr_workgroup_id_x 1
		.amdhsa_system_sgpr_workgroup_id_y 0
		.amdhsa_system_sgpr_workgroup_id_z 0
		.amdhsa_system_sgpr_workgroup_info 0
		.amdhsa_system_vgpr_workitem_id 2
		.amdhsa_next_free_vgpr 252
		.amdhsa_next_free_sgpr 98
		.amdhsa_accum_offset 252
		.amdhsa_reserve_vcc 1
		.amdhsa_float_round_mode_32 0
		.amdhsa_float_round_mode_16_64 0
		.amdhsa_float_denorm_mode_32 3
		.amdhsa_float_denorm_mode_16_64 3
		.amdhsa_dx10_clamp 1
		.amdhsa_ieee_mode 1
		.amdhsa_fp16_overflow 0
		.amdhsa_tg_split 0
		.amdhsa_exception_fp_ieee_invalid_op 0
		.amdhsa_exception_fp_denorm_src 0
		.amdhsa_exception_fp_ieee_div_zero 0
		.amdhsa_exception_fp_ieee_overflow 0
		.amdhsa_exception_fp_ieee_underflow 0
		.amdhsa_exception_fp_ieee_inexact 0
		.amdhsa_exception_int_div_zero 0
	.end_amdhsa_kernel

; __global__ void __launch_bounds__(NWAVES * 64, 2) mega(Args args) {
amdhsa.kernels:
  - .agpr_count:     0
    .args:
      - .offset:         0
        .size:           160
        .value_kind:     by_value
      - .offset:         160
        .size:           4
        .value_kind:     hidden_block_count_x
      - .offset:         164
        .size:           4
        .value_kind:     hidden_block_count_y
      - .offset:         168
        .size:           4
        .value_kind:     hidden_block_count_z
      - .offset:         172
        .size:           2
        .value_kind:     hidden_group_size_x
      - .offset:         174
        .size:           2
        .value_kind:     hidden_group_size_y
      - .offset:         176
        .size:           2
        .value_kind:     hidden_group_size_z
      - .offset:         178
        .size:           2
        .value_kind:     hidden_remainder_x
      - .offset:         180
        .size:           2
        .value_kind:     hidden_remainder_y
      - .offset:         182
        .size:           2
        .value_kind:     hidden_remainder_z
      - .offset:         200
        .size:           8
        .value_kind:     hidden_global_offset_x
      - .offset:         208
        .size:           8
        .value_kind:     hidden_global_offset_y
      - .offset:         216
        .size:           8
        .value_kind:     hidden_global_offset_z
      - .offset:         224
        .size:           2
        .value_kind:     hidden_grid_dims
      - .offset:         248
        .size:           8
        .value_kind:     hidden_multigrid_sync_arg
      - .offset:         280
        .size:           4
        .value_kind:     hidden_dynamic_lds_size
    .group_segment_fixed_size: 0
    .kernarg_segment_align: 8
    .kernarg_segment_size: 416
    .language:       OpenCL C
    .language_version:
      - 2
      - 0
    .max_flat_workgroup_size: 512
    .name:           _Z4mega4Args
    .private_segment_fixed_size: 0
    .sgpr_count:     104
    .sgpr_spill_count: 78
    .symbol:         _Z4mega4Args.kd
    .uniform_work_group_size: 1
    .uses_dynamic_stack: false
    .vgpr_count:     252
    .vgpr_spill_count: 0
    .wavefront_size: 64
